# early asynchronous L2 write-back by each XCD first arriver in the four write-back phases
# baseline (speedup 1.0000x reference)
.LBB0_522:
	s_waitcnt vmcnt(0)
	v_readfirstlane_b32 s2, v18
	v_readfirstlane_b32 s3, v3
	v_readlane_b32 s22, v255, 21
	s_add_i32 s2, s2, 1
	s_add_i32 s23, s22, 1
	s_mul_i32 s28, s3, s22
	s_add_i32 s28, s28, 1
	s_mul_i32 s3, s3, s23
	v_writelane_b32 v255, s23, 21
	v_mov_b32_e32 v0, s22
	s_cmp_lg_u32 s2, s3
	s_cbranch_scc1 .Lxb_fol
	s_cmp_eq_u32 s41, 1
	s_cbranch_scc1 .Lxb_wb
	s_cmp_eq_u32 s41, 7
	s_cbranch_scc1 .Lxb_wb
	s_cmp_eq_u32 s41, 11
	s_cbranch_scc1 .Lxb_wb
	s_cmp_eq_u32 s41, 21
	s_cbranch_scc0 .Lxb_nowb

.Lxb_nowb:
	s_waitcnt vmcnt(0)
	s_add_u32 s28, s62, 0xfa92400
	s_addc_u32 s29, s63, 0
	global_atomic_add v1, v243, s[28:29]
	global_atomic_add v1, v243, s[28:29] offset:256
	global_atomic_add v1, v243, s[28:29] offset:512
	global_atomic_add v1, v243, s[28:29] offset:768
	global_atomic_add v1, v243, s[28:29] offset:1024
	global_atomic_add v1, v243, s[28:29] offset:1280
	global_atomic_add v1, v243, s[28:29] offset:1536
	global_atomic_add v1, v243, s[28:29] offset:1792
	global_atomic_add v1, v243, s[28:29] offset:2048
	global_atomic_add v1, v243, s[28:29] offset:2304
	global_atomic_add v1, v243, s[28:29] offset:2560
	global_atomic_add v1, v243, s[28:29] offset:2816
	global_atomic_add v1, v243, s[28:29] offset:3072
	global_atomic_add v1, v243, s[28:29] offset:3328
	global_atomic_add v1, v243, s[28:29] offset:3584
	global_atomic_add v1, v243, s[28:29] offset:3840
	s_branch .Lxb_poll
.Lxb_fol:
	s_cmp_lg_u32 s2, s28
	s_cbranch_scc1 .Lxb_poll
	s_cmp_eq_u32 s41, 1
	s_cbranch_scc1 .Lxb_hwb
	s_cmp_eq_u32 s41, 7
	s_cbranch_scc1 .Lxb_hwb
	s_cmp_eq_u32 s41, 11
	s_cbranch_scc1 .Lxb_hwb
	s_cmp_eq_u32 s41, 21
	s_cbranch_scc0 .Lxb_poll
.Lxb_hwb:
	buffer_wbl2 sc1
.Lxb_poll:
	v_readlane_b32 s20, v253, 17
	v_readlane_b32 s21, v253, 18
	s_waitcnt lgkmcnt(0)
	s_nop 3
	v_add_u32_e32 v7, 1, v0
	v_mul_lo_u32 v7, v7, v2
	global_load_dword v2, v1, s[20:21] sc1
	s_waitcnt vmcnt(0)
	v_sub_u32_e32 v2, v2, v7
	v_cmp_gt_i32_e32 vcc, 0, v2
	s_and_saveexec_b64 s[20:21], vcc
	s_cbranch_execz .LBB0_537
	s_mov_b32 s35, 1
	s_mov_b64 s[22:23], 0
	s_branch .LBB0_528
